# Down1 epilogue: stash the 8 row-statistic atomics in LDS and issue them together at the end of the epilogue (on top of v3)
# speedup vs baseline: 1.0183x; 1.0039x over previous
; __device__ __forceinline__ unsigned cvt_pk_bf16(float lo, float hi) { unsigned r; asm volatile("v_cvt_pk_bf16_f32 %0, %1, %2" : "=v"(r) : "v"(lo), "v"(hi)); return r; }
;     __device__ __forceinline__ void operator()(const f32x4 (&acc)[2][2][4][2], const Unit& u, int wr, int wc, int fr, int fq) const {
;     ...
;             for (int m = 0; m < 4; ++m) {
;                 const int row = row0 + ai * HALF + m * 16;
;                 const float lrr = lz_ss ? rsqrtf(lr[ai][m] * (1.0f / DM) + RMS_EPS) : 1.0f;
;                 float s1 = 0.f, s2 = 0.f;
; #pragma unroll
;                 for (int bj = 0; bj < 2; ++bj) {
;                     const int col = col0 + bj * HALF; const size_t off = (size_t)row * DM + col;
;                     f32x4 r0, r1;
;                     if (resid_f32) { r0 = *(const f32x4*)(resid_f32 + off); r1 = *(const f32x4*)(resid_f32 + off + 4); }
;                     else { const u32x4 q = qb[m][bj];
;                         r0 = (f32x4){__uint_as_float(q.x << 16), __uint_as_float(q.x & 0xffff0000u), __uint_as_float(q.y << 16), __uint_as_float(q.y & 0xffff0000u)};
;                         r1 = (f32x4){__uint_as_float(q.z << 16), __uint_as_float(q.z & 0xffff0000u), __uint_as_float(q.w << 16), __uint_as_float(q.w & 0xffff0000u)}; }
;                     if (lz_ss) { const f32x4 g0 = *(const f32x4*)(lz_g + col), g1 = *(const f32x4*)(lz_g + col + 4); r0 = r0 * g0 * lrr; r1 = r1 * g1 * lrr; }
;                     const f32x4 x0 = r0 + acc[ai][bj][m][0] * alpha, x1 = r1 + acc[ai][bj][m][1] * alpha;
;                     u32x4 w; w.x = cvt_pk_bf16(x0[0], x0[1]); w.y = cvt_pk_bf16(x0[2], x0[3]); w.z = cvt_pk_bf16(x1[0], x1[1]); w.w = cvt_pk_bf16(x1[2], x1[3]);
;                     *(u32x4*)(xb + off) = w;
;                     s1 += ((x0[0] * x0[0] + x0[1] * x0[1]) + (x0[2] * x0[2] + x0[3] * x0[3])) + ((x1[0] * x1[0] + x1[1] * x1[1]) + (x1[2] * x1[2] + x1[3] * x1[3]));
;                     if (ss2) { const f32x4 a0 = *(const f32x4*)(ga + col), a1 = *(const f32x4*)(ga + col + 4); const f32x4 y0 = x0 * a0, y1 = x1 * a1;
;                         s2 += ((y0[0] * y0[0] + y0[1] * y0[1]) + (y0[2] * y0[2] + y0[3] * y0[3])) + ((y1[0] * y1[0] + y1[1] * y1[1]) + (y1[2] * y1[2] + y1[3] * y1[3])); }
;                 }
;                 s1 += __shfl_xor(s1, 16); s1 += __shfl_xor(s1, 32);
;                 if (fq == 0) ss_add(ss1 + row, s1);
.LBB0_826:
	s_waitcnt vmcnt(0)
	v_pk_fma_f32 v[152:153], v[152:153], 0.5, v[160:161] op_sel_hi:[1,0,1]
	v_pk_fma_f32 v[150:151], v[150:151], 0.5, v[158:159] op_sel_hi:[1,0,1]
	v_pk_fma_f32 v[154:155], v[146:147], 0.5, v[154:155] op_sel_hi:[1,0,1]
	v_mul_f32_e32 v146, v151, v151
	v_mul_f32_e32 v147, v153, v153
	v_pk_fma_f32 v[156:157], v[148:149], 0.5, v[156:157] op_sel_hi:[1,0,1]
	v_fmac_f32_e32 v146, v150, v150
	v_fmac_f32_e32 v147, v152, v152
	v_add_f32_e32 v146, v146, v147
	v_mul_f32_e32 v147, v155, v155
	v_mul_f32_e32 v148, v157, v157
	v_fmac_f32_e32 v147, v154, v154
	v_fmac_f32_e32 v148, v156, v156
	v_mul_f32_e32 v207, v217, v217
	v_mul_f32_e32 v169, v169, v169
	v_mul_f32_e32 v167, v167, v167
	v_mul_f32_e32 v165, v165, v165
	v_add_f32_e32 v147, v147, v148
	v_and_b32_e32 v148, 64, v224
	v_fmac_f32_e32 v207, v216, v216
	v_fmac_f32_e32 v169, v168, v168
	v_fmac_f32_e32 v167, v166, v166
	v_fmac_f32_e32 v165, v164, v164
	v_add_f32_e32 v146, v147, v146
	v_xor_b32_e32 v147, 16, v224
	v_add_u32_e32 v158, 64, v148
	v_add_f32_e32 v168, v207, v169
	v_add_f32_e32 v164, v167, v165
	v_cmp_lt_i32_e32 vcc, v147, v158
	v_add_f32_e32 v164, v164, v168
	v_add_f32_e32 v146, v164, v146
	v_cndmask_b32_e32 v147, v224, v147, vcc
	v_lshlrev_b32_e32 v164, 2, v147
	ds_bpermute_b32 v147, v164, v146
	v_cvt_pk_bf16_f32 v148, v150, v151
	v_cvt_pk_bf16_f32 v149, v152, v153
	v_cvt_pk_bf16_f32 v150, v154, v155
	v_lshl_add_u64 v[154:155], v[202:203], 3, s[96:97]
	s_waitcnt lgkmcnt(0)
	v_add_f32_e32 v146, v146, v147
	v_xor_b32_e32 v147, 32, v224
	v_cmp_lt_i32_e32 vcc, v147, v158
	v_cvt_pk_bf16_f32 v151, v156, v157
	global_store_dwordx4 v[162:163], v[148:151], off offset:256
	s_nop 0
	v_cndmask_b32_e32 v147, v224, v147, vcc
	v_lshlrev_b32_e32 v165, 2, v147
	ds_bpermute_b32 v147, v165, v146
	s_and_saveexec_b64 s[6:7], s[54:55]
	s_cbranch_execz .LBB0_828
	s_waitcnt lgkmcnt(0)
	v_add_f32_e32 v146, v146, v147
	v_mul_f32_e32 v146, 0x49800000, v146
	v_rndne_f32_e32 v146, v146
	v_mul_f32_e64 v147, |v146|, s90
	v_floor_f32_e32 v147, v147
	v_fma_f32 v148, v147, s91, |v146|
	v_cvt_u32_f32_e32 v148, v148
	v_cvt_u32_f32_e32 v147, v147
	v_ashrrev_i32_e32 v149, 31, v146
	v_xor_b32_e32 v146, v148, v149
	v_xor_b32_e32 v147, v147, v149
	v_sub_co_u32_e32 v146, vcc, v146, v149
	s_nop 1
	v_subb_co_u32_e32 v147, vcc, v147, v149, vcc
	v_mbcnt_lo_u32_b32 v149, -1, 0
	v_lshlrev_b32_e32 v149, 3, v149
	v_add_u32_e32 v149, s24, v149
	v_add_u32_e32 v149, 0x20c00, v149
	ds_write_b64 v149, v[146:147]

; __device__ __forceinline__ unsigned cvt_pk_bf16(float lo, float hi) { unsigned r; asm volatile("v_cvt_pk_bf16_f32 %0, %1, %2" : "=v"(r) : "v"(lo), "v"(hi)); return r; }
;     __device__ __forceinline__ void operator()(const f32x4 (&acc)[2][2][4][2], const Unit& u, int wr, int wc, int fr, int fq) const {
;     ...
;             for (int m = 0; m < 4; ++m) {
;                 const int row = row0 + ai * HALF + m * 16;
;                 const float lrr = lz_ss ? rsqrtf(lr[ai][m] * (1.0f / DM) + RMS_EPS) : 1.0f;
;                 float s1 = 0.f, s2 = 0.f;
; #pragma unroll
;                 for (int bj = 0; bj < 2; ++bj) {
;                     const int col = col0 + bj * HALF; const size_t off = (size_t)row * DM + col;
;                     f32x4 r0, r1;
;                     if (resid_f32) { r0 = *(const f32x4*)(resid_f32 + off); r1 = *(const f32x4*)(resid_f32 + off + 4); }
;                     else { const u32x4 q = qb[m][bj];
;                         r0 = (f32x4){__uint_as_float(q.x << 16), __uint_as_float(q.x & 0xffff0000u), __uint_as_float(q.y << 16), __uint_as_float(q.y & 0xffff0000u)};
;                         r1 = (f32x4){__uint_as_float(q.z << 16), __uint_as_float(q.z & 0xffff0000u), __uint_as_float(q.w << 16), __uint_as_float(q.w & 0xffff0000u)}; }
;                     if (lz_ss) { const f32x4 g0 = *(const f32x4*)(lz_g + col), g1 = *(const f32x4*)(lz_g + col + 4); r0 = r0 * g0 * lrr; r1 = r1 * g1 * lrr; }
;                     const f32x4 x0 = r0 + acc[ai][bj][m][0] * alpha, x1 = r1 + acc[ai][bj][m][1] * alpha;
;                     u32x4 w; w.x = cvt_pk_bf16(x0[0], x0[1]); w.y = cvt_pk_bf16(x0[2], x0[3]); w.z = cvt_pk_bf16(x1[0], x1[1]); w.w = cvt_pk_bf16(x1[2], x1[3]);
;                     *(u32x4*)(xb + off) = w;
;                     s1 += ((x0[0] * x0[0] + x0[1] * x0[1]) + (x0[2] * x0[2] + x0[3] * x0[3])) + ((x1[0] * x1[0] + x1[1] * x1[1]) + (x1[2] * x1[2] + x1[3] * x1[3]));
;                     if (ss2) { const f32x4 a0 = *(const f32x4*)(ga + col), a1 = *(const f32x4*)(ga + col + 4); const f32x4 y0 = x0 * a0, y1 = x1 * a1;
;                         s2 += ((y0[0] * y0[0] + y0[1] * y0[1]) + (y0[2] * y0[2] + y0[3] * y0[3])) + ((y1[0] * y1[0] + y1[1] * y1[1]) + (y1[2] * y1[2] + y1[3] * y1[3])); }
;                 }
;                 s1 += __shfl_xor(s1, 16); s1 += __shfl_xor(s1, 32);
;                 if (fq == 0) ss_add(ss1 + row, s1);
.LBB0_838:
	s_waitcnt vmcnt(0)
	v_pk_fma_f32 v[136:137], v[136:137], 0.5, v[144:145] op_sel_hi:[1,0,1]
	v_pk_fma_f32 v[134:135], v[134:135], 0.5, v[142:143] op_sel_hi:[1,0,1]
	v_pk_fma_f32 v[138:139], v[130:131], 0.5, v[138:139] op_sel_hi:[1,0,1]
	v_mul_f32_e32 v130, v135, v135
	v_mul_f32_e32 v131, v137, v137
	v_pk_fma_f32 v[140:141], v[132:133], 0.5, v[140:141] op_sel_hi:[1,0,1]
	v_fmac_f32_e32 v130, v134, v134
	v_fmac_f32_e32 v131, v136, v136
	v_mul_f32_e32 v156, v163, v163
	v_mul_f32_e32 v153, v153, v153
	v_mul_f32_e32 v151, v151, v151
	v_mul_f32_e32 v149, v149, v149
	v_add_f32_e32 v130, v130, v131
	v_mul_f32_e32 v131, v139, v139
	v_mul_f32_e32 v132, v141, v141
	v_fmac_f32_e32 v156, v162, v162
	v_fmac_f32_e32 v153, v152, v152
	v_fmac_f32_e32 v151, v150, v150
	v_fmac_f32_e32 v149, v148, v148
	v_fmac_f32_e32 v131, v138, v138
	v_fmac_f32_e32 v132, v140, v140
	v_add_f32_e32 v152, v156, v153
	v_add_f32_e32 v148, v151, v149
	v_add_f32_e32 v131, v131, v132
	v_add_f32_e32 v148, v148, v152
	v_add_f32_e32 v130, v131, v130
	v_add_f32_e32 v130, v148, v130
	ds_bpermute_b32 v131, v164, v130
	v_cvt_pk_bf16_f32 v132, v134, v135
	v_cvt_pk_bf16_f32 v133, v136, v137
	v_cvt_pk_bf16_f32 v134, v138, v139
	v_cvt_pk_bf16_f32 v135, v140, v141
	s_waitcnt lgkmcnt(0)
	v_add_f32_e32 v130, v130, v131
	ds_bpermute_b32 v131, v165, v130
	global_store_dwordx4 v[146:147], v[132:135], off offset:256
	s_and_saveexec_b64 s[6:7], s[54:55]
	s_cbranch_execz .LBB0_840
	s_waitcnt lgkmcnt(0)
	v_add_f32_e32 v130, v130, v131
	v_mul_f32_e32 v130, 0x49800000, v130
	v_rndne_f32_e32 v130, v130
	v_mul_f32_e64 v131, |v130|, s90
	v_floor_f32_e32 v131, v131
	v_fma_f32 v132, v131, s91, |v130|
	v_cvt_u32_f32_e32 v132, v132
	v_cvt_u32_f32_e32 v131, v131
	v_ashrrev_i32_e32 v133, 31, v130
	v_xor_b32_e32 v130, v132, v133
	v_xor_b32_e32 v131, v131, v133
	v_sub_co_u32_e32 v130, vcc, v130, v133
	s_nop 1
	v_subb_co_u32_e32 v131, vcc, v131, v133, vcc
	v_mbcnt_lo_u32_b32 v133, -1, 0
	v_lshlrev_b32_e32 v133, 3, v133
	v_add_u32_e32 v133, s24, v133
	v_add_u32_e32 v133, 0x20c00, v133
	ds_write_b64 v133, v[130:131] offset:128

; __device__ __forceinline__ unsigned cvt_pk_bf16(float lo, float hi) { unsigned r; asm volatile("v_cvt_pk_bf16_f32 %0, %1, %2" : "=v"(r) : "v"(lo), "v"(hi)); return r; }
;     __device__ __forceinline__ void operator()(const f32x4 (&acc)[2][2][4][2], const Unit& u, int wr, int wc, int fr, int fq) const {
;     ...
;             for (int m = 0; m < 4; ++m) {
;                 const int row = row0 + ai * HALF + m * 16;
;                 const float lrr = lz_ss ? rsqrtf(lr[ai][m] * (1.0f / DM) + RMS_EPS) : 1.0f;
;                 float s1 = 0.f, s2 = 0.f;
; #pragma unroll
;                 for (int bj = 0; bj < 2; ++bj) {
;                     const int col = col0 + bj * HALF; const size_t off = (size_t)row * DM + col;
;                     f32x4 r0, r1;
;                     if (resid_f32) { r0 = *(const f32x4*)(resid_f32 + off); r1 = *(const f32x4*)(resid_f32 + off + 4); }
;                     else { const u32x4 q = qb[m][bj];
;                         r0 = (f32x4){__uint_as_float(q.x << 16), __uint_as_float(q.x & 0xffff0000u), __uint_as_float(q.y << 16), __uint_as_float(q.y & 0xffff0000u)};
;                         r1 = (f32x4){__uint_as_float(q.z << 16), __uint_as_float(q.z & 0xffff0000u), __uint_as_float(q.w << 16), __uint_as_float(q.w & 0xffff0000u)}; }
;                     if (lz_ss) { const f32x4 g0 = *(const f32x4*)(lz_g + col), g1 = *(const f32x4*)(lz_g + col + 4); r0 = r0 * g0 * lrr; r1 = r1 * g1 * lrr; }
;                     const f32x4 x0 = r0 + acc[ai][bj][m][0] * alpha, x1 = r1 + acc[ai][bj][m][1] * alpha;
;                     u32x4 w; w.x = cvt_pk_bf16(x0[0], x0[1]); w.y = cvt_pk_bf16(x0[2], x0[3]); w.z = cvt_pk_bf16(x1[0], x1[1]); w.w = cvt_pk_bf16(x1[2], x1[3]);
;                     *(u32x4*)(xb + off) = w;
;                     s1 += ((x0[0] * x0[0] + x0[1] * x0[1]) + (x0[2] * x0[2] + x0[3] * x0[3])) + ((x1[0] * x1[0] + x1[1] * x1[1]) + (x1[2] * x1[2] + x1[3] * x1[3]));
;                     if (ss2) { const f32x4 a0 = *(const f32x4*)(ga + col), a1 = *(const f32x4*)(ga + col + 4); const f32x4 y0 = x0 * a0, y1 = x1 * a1;
;                         s2 += ((y0[0] * y0[0] + y0[1] * y0[1]) + (y0[2] * y0[2] + y0[3] * y0[3])) + ((y1[0] * y1[0] + y1[1] * y1[1]) + (y1[2] * y1[2] + y1[3] * y1[3])); }
;                 }
;                 s1 += __shfl_xor(s1, 16); s1 += __shfl_xor(s1, 32);
;                 if (fq == 0) ss_add(ss1 + row, s1);
.LBB0_850:
	s_waitcnt vmcnt(0)
	v_pk_fma_f32 v[112:113], v[112:113], 0.5, v[124:125] op_sel_hi:[1,0,1]
	v_pk_fma_f32 v[110:111], v[110:111], 0.5, v[122:123] op_sel_hi:[1,0,1]
	v_pk_fma_f32 v[118:119], v[106:107], 0.5, v[118:119] op_sel_hi:[1,0,1]
	v_mul_f32_e32 v106, v111, v111
	v_mul_f32_e32 v107, v113, v113
	v_pk_fma_f32 v[120:121], v[108:109], 0.5, v[120:121] op_sel_hi:[1,0,1]
	v_fmac_f32_e32 v106, v110, v110
	v_fmac_f32_e32 v107, v112, v112
	v_mul_f32_e32 v138, v145, v145
	v_mul_f32_e32 v137, v137, v137
	v_mul_f32_e32 v135, v135, v135
	v_mul_f32_e32 v133, v133, v133
	v_add_f32_e32 v106, v106, v107
	v_mul_f32_e32 v107, v119, v119
	v_mul_f32_e32 v108, v121, v121
	v_fmac_f32_e32 v138, v144, v144
	v_fmac_f32_e32 v137, v136, v136
	v_fmac_f32_e32 v135, v134, v134
	v_fmac_f32_e32 v133, v132, v132
	v_fmac_f32_e32 v107, v118, v118
	v_fmac_f32_e32 v108, v120, v120
	v_add_f32_e32 v136, v138, v137
	v_add_f32_e32 v132, v135, v133
	v_add_f32_e32 v107, v107, v108
	v_add_f32_e32 v132, v132, v136
	v_add_f32_e32 v106, v107, v106
	v_add_f32_e32 v106, v132, v106
	ds_bpermute_b32 v107, v164, v106
	v_cvt_pk_bf16_f32 v108, v110, v111
	v_cvt_pk_bf16_f32 v109, v112, v113
	v_cvt_pk_bf16_f32 v110, v118, v119
	v_cvt_pk_bf16_f32 v111, v120, v121
	s_waitcnt lgkmcnt(0)
	v_add_f32_e32 v106, v106, v107
	ds_bpermute_b32 v107, v165, v106
	global_store_dwordx4 v[130:131], v[108:111], off offset:256
	s_and_saveexec_b64 s[6:7], s[54:55]
	s_cbranch_execz .LBB0_852
	s_waitcnt lgkmcnt(0)
	v_add_f32_e32 v106, v106, v107
	v_mul_f32_e32 v106, 0x49800000, v106
	v_rndne_f32_e32 v106, v106
	v_mul_f32_e64 v107, |v106|, s90
	v_floor_f32_e32 v107, v107
	v_fma_f32 v108, v107, s91, |v106|
	v_cvt_u32_f32_e32 v108, v108
	v_cvt_u32_f32_e32 v107, v107
	v_ashrrev_i32_e32 v109, 31, v106
	v_xor_b32_e32 v106, v108, v109
	v_xor_b32_e32 v107, v107, v109
	v_sub_co_u32_e32 v106, vcc, v106, v109
	s_nop 1
	v_subb_co_u32_e32 v107, vcc, v107, v109, vcc
	v_mbcnt_lo_u32_b32 v109, -1, 0
	v_lshlrev_b32_e32 v109, 3, v109
	v_add_u32_e32 v109, s24, v109
	v_add_u32_e32 v109, 0x20c00, v109
	ds_write_b64 v109, v[106:107] offset:256

; __device__ __forceinline__ unsigned cvt_pk_bf16(float lo, float hi) { unsigned r; asm volatile("v_cvt_pk_bf16_f32 %0, %1, %2" : "=v"(r) : "v"(lo), "v"(hi)); return r; }
;     __device__ __forceinline__ void operator()(const f32x4 (&acc)[2][2][4][2], const Unit& u, int wr, int wc, int fr, int fq) const {
;     ...
;             for (int m = 0; m < 4; ++m) {
;                 const int row = row0 + ai * HALF + m * 16;
;                 const float lrr = lz_ss ? rsqrtf(lr[ai][m] * (1.0f / DM) + RMS_EPS) : 1.0f;
;                 float s1 = 0.f, s2 = 0.f;
; #pragma unroll
;                 for (int bj = 0; bj < 2; ++bj) {
;                     const int col = col0 + bj * HALF; const size_t off = (size_t)row * DM + col;
;                     f32x4 r0, r1;
;                     if (resid_f32) { r0 = *(const f32x4*)(resid_f32 + off); r1 = *(const f32x4*)(resid_f32 + off + 4); }
;                     else { const u32x4 q = qb[m][bj];
;                         r0 = (f32x4){__uint_as_float(q.x << 16), __uint_as_float(q.x & 0xffff0000u), __uint_as_float(q.y << 16), __uint_as_float(q.y & 0xffff0000u)};
;                         r1 = (f32x4){__uint_as_float(q.z << 16), __uint_as_float(q.z & 0xffff0000u), __uint_as_float(q.w << 16), __uint_as_float(q.w & 0xffff0000u)}; }
;                     if (lz_ss) { const f32x4 g0 = *(const f32x4*)(lz_g + col), g1 = *(const f32x4*)(lz_g + col + 4); r0 = r0 * g0 * lrr; r1 = r1 * g1 * lrr; }
;                     const f32x4 x0 = r0 + acc[ai][bj][m][0] * alpha, x1 = r1 + acc[ai][bj][m][1] * alpha;
;                     u32x4 w; w.x = cvt_pk_bf16(x0[0], x0[1]); w.y = cvt_pk_bf16(x0[2], x0[3]); w.z = cvt_pk_bf16(x1[0], x1[1]); w.w = cvt_pk_bf16(x1[2], x1[3]);
;                     *(u32x4*)(xb + off) = w;
;                     s1 += ((x0[0] * x0[0] + x0[1] * x0[1]) + (x0[2] * x0[2] + x0[3] * x0[3])) + ((x1[0] * x1[0] + x1[1] * x1[1]) + (x1[2] * x1[2] + x1[3] * x1[3]));
;                     if (ss2) { const f32x4 a0 = *(const f32x4*)(ga + col), a1 = *(const f32x4*)(ga + col + 4); const f32x4 y0 = x0 * a0, y1 = x1 * a1;
;                         s2 += ((y0[0] * y0[0] + y0[1] * y0[1]) + (y0[2] * y0[2] + y0[3] * y0[3])) + ((y1[0] * y1[0] + y1[1] * y1[1]) + (y1[2] * y1[2] + y1[3] * y1[3])); }
;                 }
;                 s1 += __shfl_xor(s1, 16); s1 += __shfl_xor(s1, 32);
;                 if (fq == 0) ss_add(ss1 + row, s1);
.LBB0_862:
	s_waitcnt vmcnt(0)
	v_pk_fma_f32 v[88:89], v[88:89], 0.5, v[100:101] op_sel_hi:[1,0,1]
	v_pk_fma_f32 v[86:87], v[86:87], 0.5, v[98:99] op_sel_hi:[1,0,1]
	v_pk_fma_f32 v[94:95], v[82:83], 0.5, v[94:95] op_sel_hi:[1,0,1]
	v_mul_f32_e32 v82, v87, v87
	v_mul_f32_e32 v83, v89, v89
	v_pk_fma_f32 v[96:97], v[84:85], 0.5, v[96:97] op_sel_hi:[1,0,1]
	v_fmac_f32_e32 v82, v86, v86
	v_fmac_f32_e32 v83, v88, v88
	v_mul_f32_e32 v118, v125, v125
	v_mul_f32_e32 v113, v113, v113
	v_mul_f32_e32 v111, v111, v111
	v_mul_f32_e32 v109, v109, v109
	v_add_f32_e32 v82, v82, v83
	v_mul_f32_e32 v83, v95, v95
	v_mul_f32_e32 v84, v97, v97
	v_fmac_f32_e32 v118, v124, v124
	v_fmac_f32_e32 v113, v112, v112
	v_fmac_f32_e32 v111, v110, v110
	v_fmac_f32_e32 v109, v108, v108
	v_fmac_f32_e32 v83, v94, v94
	v_fmac_f32_e32 v84, v96, v96
	v_add_f32_e32 v112, v118, v113
	v_add_f32_e32 v108, v111, v109
	v_add_f32_e32 v83, v83, v84
	v_add_f32_e32 v108, v108, v112
	v_add_f32_e32 v82, v83, v82
	v_add_f32_e32 v82, v108, v82
	ds_bpermute_b32 v83, v164, v82
	v_cvt_pk_bf16_f32 v84, v86, v87
	v_cvt_pk_bf16_f32 v85, v88, v89
	v_cvt_pk_bf16_f32 v86, v94, v95
	v_cvt_pk_bf16_f32 v87, v96, v97
	s_waitcnt lgkmcnt(0)
	v_add_f32_e32 v82, v82, v83
	ds_bpermute_b32 v83, v165, v82
	global_store_dwordx4 v[106:107], v[84:87], off offset:256
	s_and_saveexec_b64 s[6:7], s[54:55]
	s_cbranch_execz .LBB0_864
	s_waitcnt lgkmcnt(0)
	v_add_f32_e32 v82, v82, v83
	v_mul_f32_e32 v82, 0x49800000, v82
	v_rndne_f32_e32 v82, v82
	v_mul_f32_e64 v83, |v82|, s90
	v_floor_f32_e32 v83, v83
	v_fma_f32 v84, v83, s91, |v82|
	v_cvt_u32_f32_e32 v84, v84
	v_cvt_u32_f32_e32 v83, v83
	v_ashrrev_i32_e32 v85, 31, v82
	v_xor_b32_e32 v82, v84, v85
	v_xor_b32_e32 v83, v83, v85
	v_sub_co_u32_e32 v82, vcc, v82, v85
	s_nop 1
	v_subb_co_u32_e32 v83, vcc, v83, v85, vcc
	v_mbcnt_lo_u32_b32 v85, -1, 0
	v_lshlrev_b32_e32 v85, 3, v85
	v_add_u32_e32 v85, s24, v85
	v_add_u32_e32 v85, 0x20c00, v85
	ds_write_b64 v85, v[82:83] offset:384

; __device__ __forceinline__ unsigned cvt_pk_bf16(float lo, float hi) { unsigned r; asm volatile("v_cvt_pk_bf16_f32 %0, %1, %2" : "=v"(r) : "v"(lo), "v"(hi)); return r; }
;     __device__ __forceinline__ void operator()(const f32x4 (&acc)[2][2][4][2], const Unit& u, int wr, int wc, int fr, int fq) const {
;     ...
;             for (int m = 0; m < 4; ++m) {
;                 const int row = row0 + ai * HALF + m * 16;
;                 const float lrr = lz_ss ? rsqrtf(lr[ai][m] * (1.0f / DM) + RMS_EPS) : 1.0f;
;                 float s1 = 0.f, s2 = 0.f;
; #pragma unroll
;                 for (int bj = 0; bj < 2; ++bj) {
;                     const int col = col0 + bj * HALF; const size_t off = (size_t)row * DM + col;
;                     f32x4 r0, r1;
;                     if (resid_f32) { r0 = *(const f32x4*)(resid_f32 + off); r1 = *(const f32x4*)(resid_f32 + off + 4); }
;                     else { const u32x4 q = qb[m][bj];
;                         r0 = (f32x4){__uint_as_float(q.x << 16), __uint_as_float(q.x & 0xffff0000u), __uint_as_float(q.y << 16), __uint_as_float(q.y & 0xffff0000u)};
;                         r1 = (f32x4){__uint_as_float(q.z << 16), __uint_as_float(q.z & 0xffff0000u), __uint_as_float(q.w << 16), __uint_as_float(q.w & 0xffff0000u)}; }
;                     if (lz_ss) { const f32x4 g0 = *(const f32x4*)(lz_g + col), g1 = *(const f32x4*)(lz_g + col + 4); r0 = r0 * g0 * lrr; r1 = r1 * g1 * lrr; }
;                     const f32x4 x0 = r0 + acc[ai][bj][m][0] * alpha, x1 = r1 + acc[ai][bj][m][1] * alpha;
;                     u32x4 w; w.x = cvt_pk_bf16(x0[0], x0[1]); w.y = cvt_pk_bf16(x0[2], x0[3]); w.z = cvt_pk_bf16(x1[0], x1[1]); w.w = cvt_pk_bf16(x1[2], x1[3]);
;                     *(u32x4*)(xb + off) = w;
;                     s1 += ((x0[0] * x0[0] + x0[1] * x0[1]) + (x0[2] * x0[2] + x0[3] * x0[3])) + ((x1[0] * x1[0] + x1[1] * x1[1]) + (x1[2] * x1[2] + x1[3] * x1[3]));
;                     if (ss2) { const f32x4 a0 = *(const f32x4*)(ga + col), a1 = *(const f32x4*)(ga + col + 4); const f32x4 y0 = x0 * a0, y1 = x1 * a1;
;                         s2 += ((y0[0] * y0[0] + y0[1] * y0[1]) + (y0[2] * y0[2] + y0[3] * y0[3])) + ((y1[0] * y1[0] + y1[1] * y1[1]) + (y1[2] * y1[2] + y1[3] * y1[3])); }
;                 }
;                 s1 += __shfl_xor(s1, 16); s1 += __shfl_xor(s1, 32);
;                 if (fq == 0) ss_add(ss1 + row, s1);
.LBB0_878:
	s_waitcnt vmcnt(0)
	v_pk_fma_f32 v[60:61], v[60:61], 0.5, v[72:73] op_sel_hi:[1,0,1]
	v_pk_fma_f32 v[58:59], v[58:59], 0.5, v[70:71] op_sel_hi:[1,0,1]
	v_pk_fma_f32 v[66:67], v[54:55], 0.5, v[66:67] op_sel_hi:[1,0,1]
	v_mul_f32_e32 v54, v59, v59
	v_mul_f32_e32 v55, v61, v61
	v_pk_fma_f32 v[68:69], v[56:57], 0.5, v[68:69] op_sel_hi:[1,0,1]
	v_fmac_f32_e32 v54, v58, v58
	v_fmac_f32_e32 v55, v60, v60
	v_mul_f32_e32 v96, v107, v107
	v_mul_f32_e32 v89, v89, v89
	v_mul_f32_e32 v87, v87, v87
	v_mul_f32_e32 v85, v85, v85
	v_add_f32_e32 v54, v54, v55
	v_mul_f32_e32 v55, v67, v67
	v_mul_f32_e32 v56, v69, v69
	v_fmac_f32_e32 v96, v106, v106
	v_fmac_f32_e32 v89, v88, v88
	v_fmac_f32_e32 v87, v86, v86
	v_fmac_f32_e32 v85, v84, v84
	v_fmac_f32_e32 v55, v66, v66
	v_fmac_f32_e32 v56, v68, v68
	v_add_f32_e32 v88, v96, v89
	v_add_f32_e32 v84, v87, v85
	v_add_f32_e32 v55, v55, v56
	v_add_f32_e32 v84, v84, v88
	v_add_f32_e32 v54, v55, v54
	v_add_f32_e32 v54, v84, v54
	ds_bpermute_b32 v55, v164, v54
	v_cvt_pk_bf16_f32 v56, v58, v59
	v_cvt_pk_bf16_f32 v57, v60, v61
	v_cvt_pk_bf16_f32 v58, v66, v67
	v_cvt_pk_bf16_f32 v59, v68, v69
	s_waitcnt lgkmcnt(0)
	v_add_f32_e32 v54, v54, v55
	ds_bpermute_b32 v55, v165, v54
	global_store_dwordx4 v[82:83], v[56:59], off offset:256
	s_and_saveexec_b64 s[6:7], s[54:55]
	s_cbranch_execz .LBB0_880
	s_waitcnt lgkmcnt(0)
	v_add_f32_e32 v54, v54, v55
	v_mul_f32_e32 v54, 0x49800000, v54
	v_rndne_f32_e32 v54, v54
	v_mul_f32_e64 v55, |v54|, s90
	v_floor_f32_e32 v55, v55
	v_fma_f32 v58, v55, s91, |v54|
	v_cvt_u32_f32_e32 v58, v58
	v_cvt_u32_f32_e32 v55, v55
	v_ashrrev_i32_e32 v59, 31, v54
	v_lshl_add_u64 v[56:57], v[94:95], 3, s[96:97]
	v_xor_b32_e32 v54, v58, v59
	v_xor_b32_e32 v55, v55, v59
	v_sub_co_u32_e32 v54, vcc, v54, v59
	s_nop 1
	v_subb_co_u32_e32 v55, vcc, v55, v59, vcc
	v_mbcnt_lo_u32_b32 v59, -1, 0
	v_lshlrev_b32_e32 v59, 3, v59
	v_add_u32_e32 v59, s24, v59
	v_add_u32_e32 v59, 0x20c00, v59
	ds_write_b64 v59, v[54:55] offset:512

; __device__ __forceinline__ unsigned cvt_pk_bf16(float lo, float hi) { unsigned r; asm volatile("v_cvt_pk_bf16_f32 %0, %1, %2" : "=v"(r) : "v"(lo), "v"(hi)); return r; }
;     __device__ __forceinline__ void operator()(const f32x4 (&acc)[2][2][4][2], const Unit& u, int wr, int wc, int fr, int fq) const {
;     ...
;             for (int m = 0; m < 4; ++m) {
;                 const int row = row0 + ai * HALF + m * 16;
;                 const float lrr = lz_ss ? rsqrtf(lr[ai][m] * (1.0f / DM) + RMS_EPS) : 1.0f;
;                 float s1 = 0.f, s2 = 0.f;
; #pragma unroll
;                 for (int bj = 0; bj < 2; ++bj) {
;                     const int col = col0 + bj * HALF; const size_t off = (size_t)row * DM + col;
;                     f32x4 r0, r1;
;                     if (resid_f32) { r0 = *(const f32x4*)(resid_f32 + off); r1 = *(const f32x4*)(resid_f32 + off + 4); }
;                     else { const u32x4 q = qb[m][bj];
;                         r0 = (f32x4){__uint_as_float(q.x << 16), __uint_as_float(q.x & 0xffff0000u), __uint_as_float(q.y << 16), __uint_as_float(q.y & 0xffff0000u)};
;                         r1 = (f32x4){__uint_as_float(q.z << 16), __uint_as_float(q.z & 0xffff0000u), __uint_as_float(q.w << 16), __uint_as_float(q.w & 0xffff0000u)}; }
;                     if (lz_ss) { const f32x4 g0 = *(const f32x4*)(lz_g + col), g1 = *(const f32x4*)(lz_g + col + 4); r0 = r0 * g0 * lrr; r1 = r1 * g1 * lrr; }
;                     const f32x4 x0 = r0 + acc[ai][bj][m][0] * alpha, x1 = r1 + acc[ai][bj][m][1] * alpha;
;                     u32x4 w; w.x = cvt_pk_bf16(x0[0], x0[1]); w.y = cvt_pk_bf16(x0[2], x0[3]); w.z = cvt_pk_bf16(x1[0], x1[1]); w.w = cvt_pk_bf16(x1[2], x1[3]);
;                     *(u32x4*)(xb + off) = w;
;                     s1 += ((x0[0] * x0[0] + x0[1] * x0[1]) + (x0[2] * x0[2] + x0[3] * x0[3])) + ((x1[0] * x1[0] + x1[1] * x1[1]) + (x1[2] * x1[2] + x1[3] * x1[3]));
;                     if (ss2) { const f32x4 a0 = *(const f32x4*)(ga + col), a1 = *(const f32x4*)(ga + col + 4); const f32x4 y0 = x0 * a0, y1 = x1 * a1;
;                         s2 += ((y0[0] * y0[0] + y0[1] * y0[1]) + (y0[2] * y0[2] + y0[3] * y0[3])) + ((y1[0] * y1[0] + y1[1] * y1[1]) + (y1[2] * y1[2] + y1[3] * y1[3])); }
;                 }
;                 s1 += __shfl_xor(s1, 16); s1 += __shfl_xor(s1, 32);
;                 if (fq == 0) ss_add(ss1 + row, s1);
.LBB0_890:
	s_waitcnt vmcnt(0)
	v_pk_fma_f32 v[40:41], v[40:41], 0.5, v[48:49] op_sel_hi:[1,0,1]
	v_pk_fma_f32 v[38:39], v[38:39], 0.5, v[46:47] op_sel_hi:[1,0,1]
	v_pk_fma_f32 v[42:43], v[34:35], 0.5, v[42:43] op_sel_hi:[1,0,1]
	v_mul_f32_e32 v34, v39, v39
	v_mul_f32_e32 v35, v41, v41
	v_pk_fma_f32 v[44:45], v[36:37], 0.5, v[44:45] op_sel_hi:[1,0,1]
	v_fmac_f32_e32 v34, v38, v38
	v_fmac_f32_e32 v35, v40, v40
	v_mul_f32_e32 v66, v73, v73
	v_mul_f32_e32 v61, v61, v61
	v_mul_f32_e32 v59, v59, v59
	v_mul_f32_e32 v57, v57, v57
	v_add_f32_e32 v34, v34, v35
	v_mul_f32_e32 v35, v43, v43
	v_mul_f32_e32 v36, v45, v45
	v_fmac_f32_e32 v66, v72, v72
	v_fmac_f32_e32 v61, v60, v60
	v_fmac_f32_e32 v59, v58, v58
	v_fmac_f32_e32 v57, v56, v56
	v_fmac_f32_e32 v35, v42, v42
	v_fmac_f32_e32 v36, v44, v44
	v_add_f32_e32 v60, v66, v61
	v_add_f32_e32 v56, v59, v57
	v_add_f32_e32 v35, v35, v36
	v_add_f32_e32 v56, v56, v60
	v_add_f32_e32 v34, v35, v34
	v_add_f32_e32 v34, v56, v34
	ds_bpermute_b32 v35, v164, v34
	v_cvt_pk_bf16_f32 v36, v38, v39
	v_cvt_pk_bf16_f32 v37, v40, v41
	v_cvt_pk_bf16_f32 v38, v42, v43
	v_cvt_pk_bf16_f32 v39, v44, v45
	s_waitcnt lgkmcnt(0)
	v_add_f32_e32 v34, v34, v35
	ds_bpermute_b32 v35, v165, v34
	global_store_dwordx4 v[54:55], v[36:39], off offset:256
	s_and_saveexec_b64 s[6:7], s[54:55]
	s_cbranch_execz .LBB0_892
	s_waitcnt lgkmcnt(0)
	v_add_f32_e32 v34, v34, v35
	v_mul_f32_e32 v34, 0x49800000, v34
	v_rndne_f32_e32 v34, v34
	v_mul_f32_e64 v35, |v34|, s90
	v_floor_f32_e32 v35, v35
	v_fma_f32 v36, v35, s91, |v34|
	v_cvt_u32_f32_e32 v36, v36
	v_cvt_u32_f32_e32 v35, v35
	v_ashrrev_i32_e32 v37, 31, v34
	v_xor_b32_e32 v34, v36, v37
	v_xor_b32_e32 v35, v35, v37
	v_sub_co_u32_e32 v34, vcc, v34, v37
	s_nop 1
	v_subb_co_u32_e32 v35, vcc, v35, v37, vcc
	v_mbcnt_lo_u32_b32 v37, -1, 0
	v_lshlrev_b32_e32 v37, 3, v37
	v_add_u32_e32 v37, s24, v37
	v_add_u32_e32 v37, 0x20c00, v37
	ds_write_b64 v37, v[34:35] offset:640

; __device__ __forceinline__ unsigned cvt_pk_bf16(float lo, float hi) { unsigned r; asm volatile("v_cvt_pk_bf16_f32 %0, %1, %2" : "=v"(r) : "v"(lo), "v"(hi)); return r; }
;     __device__ __forceinline__ void operator()(const f32x4 (&acc)[2][2][4][2], const Unit& u, int wr, int wc, int fr, int fq) const {
;     ...
;             for (int m = 0; m < 4; ++m) {
;                 const int row = row0 + ai * HALF + m * 16;
;                 const float lrr = lz_ss ? rsqrtf(lr[ai][m] * (1.0f / DM) + RMS_EPS) : 1.0f;
;                 float s1 = 0.f, s2 = 0.f;
; #pragma unroll
;                 for (int bj = 0; bj < 2; ++bj) {
;                     const int col = col0 + bj * HALF; const size_t off = (size_t)row * DM + col;
;                     f32x4 r0, r1;
;                     if (resid_f32) { r0 = *(const f32x4*)(resid_f32 + off); r1 = *(const f32x4*)(resid_f32 + off + 4); }
;                     else { const u32x4 q = qb[m][bj];
;                         r0 = (f32x4){__uint_as_float(q.x << 16), __uint_as_float(q.x & 0xffff0000u), __uint_as_float(q.y << 16), __uint_as_float(q.y & 0xffff0000u)};
;                         r1 = (f32x4){__uint_as_float(q.z << 16), __uint_as_float(q.z & 0xffff0000u), __uint_as_float(q.w << 16), __uint_as_float(q.w & 0xffff0000u)}; }
;                     if (lz_ss) { const f32x4 g0 = *(const f32x4*)(lz_g + col), g1 = *(const f32x4*)(lz_g + col + 4); r0 = r0 * g0 * lrr; r1 = r1 * g1 * lrr; }
;                     const f32x4 x0 = r0 + acc[ai][bj][m][0] * alpha, x1 = r1 + acc[ai][bj][m][1] * alpha;
;                     u32x4 w; w.x = cvt_pk_bf16(x0[0], x0[1]); w.y = cvt_pk_bf16(x0[2], x0[3]); w.z = cvt_pk_bf16(x1[0], x1[1]); w.w = cvt_pk_bf16(x1[2], x1[3]);
;                     *(u32x4*)(xb + off) = w;
;                     s1 += ((x0[0] * x0[0] + x0[1] * x0[1]) + (x0[2] * x0[2] + x0[3] * x0[3])) + ((x1[0] * x1[0] + x1[1] * x1[1]) + (x1[2] * x1[2] + x1[3] * x1[3]));
;                     if (ss2) { const f32x4 a0 = *(const f32x4*)(ga + col), a1 = *(const f32x4*)(ga + col + 4); const f32x4 y0 = x0 * a0, y1 = x1 * a1;
;                         s2 += ((y0[0] * y0[0] + y0[1] * y0[1]) + (y0[2] * y0[2] + y0[3] * y0[3])) + ((y1[0] * y1[0] + y1[1] * y1[1]) + (y1[2] * y1[2] + y1[3] * y1[3])); }
;                 }
;                 s1 += __shfl_xor(s1, 16); s1 += __shfl_xor(s1, 32);
;                 if (fq == 0) ss_add(ss1 + row, s1);
.LBB0_902:
	s_waitcnt vmcnt(0)
	v_pk_fma_f32 v[24:25], v[24:25], 0.5, v[32:33] op_sel_hi:[1,0,1]
	v_pk_fma_f32 v[22:23], v[22:23], 0.5, v[30:31] op_sel_hi:[1,0,1]
	v_pk_fma_f32 v[26:27], v[18:19], 0.5, v[26:27] op_sel_hi:[1,0,1]
	v_mul_f32_e32 v18, v23, v23
	v_mul_f32_e32 v19, v25, v25
	v_pk_fma_f32 v[28:29], v[20:21], 0.5, v[28:29] op_sel_hi:[1,0,1]
	v_fmac_f32_e32 v18, v22, v22
	v_fmac_f32_e32 v19, v24, v24
	v_mul_f32_e32 v42, v49, v49
	v_mul_f32_e32 v41, v41, v41
	v_mul_f32_e32 v39, v39, v39
	v_mul_f32_e32 v37, v37, v37
	v_add_f32_e32 v18, v18, v19
	v_mul_f32_e32 v19, v27, v27
	v_mul_f32_e32 v20, v29, v29
	v_fmac_f32_e32 v42, v48, v48
	v_fmac_f32_e32 v41, v40, v40
	v_fmac_f32_e32 v39, v38, v38
	v_fmac_f32_e32 v37, v36, v36
	v_fmac_f32_e32 v19, v26, v26
	v_fmac_f32_e32 v20, v28, v28
	v_add_f32_e32 v40, v42, v41
	v_add_f32_e32 v36, v39, v37
	v_add_f32_e32 v19, v19, v20
	v_add_f32_e32 v36, v36, v40
	v_add_f32_e32 v18, v19, v18
	v_add_f32_e32 v18, v36, v18
	ds_bpermute_b32 v19, v164, v18
	v_cvt_pk_bf16_f32 v20, v22, v23
	v_cvt_pk_bf16_f32 v21, v24, v25
	v_cvt_pk_bf16_f32 v22, v26, v27
	v_cvt_pk_bf16_f32 v23, v28, v29
	s_waitcnt lgkmcnt(0)
	v_add_f32_e32 v18, v18, v19
	ds_bpermute_b32 v19, v165, v18
	global_store_dwordx4 v[34:35], v[20:23], off offset:256
	s_and_saveexec_b64 s[6:7], s[54:55]
	s_cbranch_execz .LBB0_904
	s_waitcnt lgkmcnt(0)
	v_add_f32_e32 v18, v18, v19
	v_mul_f32_e32 v18, 0x49800000, v18
	v_rndne_f32_e32 v18, v18
	v_mul_f32_e64 v19, |v18|, s90
	v_floor_f32_e32 v19, v19
	v_fma_f32 v20, v19, s91, |v18|
	v_cvt_u32_f32_e32 v20, v20
	v_cvt_u32_f32_e32 v19, v19
	v_ashrrev_i32_e32 v21, 31, v18
	v_xor_b32_e32 v18, v20, v21
	v_xor_b32_e32 v19, v19, v21
	v_sub_co_u32_e32 v18, vcc, v18, v21
	s_nop 1
	v_subb_co_u32_e32 v19, vcc, v19, v21, vcc
	v_mbcnt_lo_u32_b32 v21, -1, 0
	v_lshlrev_b32_e32 v21, 3, v21
	v_add_u32_e32 v21, s24, v21
	v_add_u32_e32 v21, 0x20c00, v21
	ds_write_b64 v21, v[18:19] offset:768

;     __device__ __forceinline__ void operator()(const f32x4 (&acc)[2][2][4][2], const Unit& u, int wr, int wc, int fr, int fq) const {
;     ...
;             for (int m = 0; m < 4; ++m) {
;                 const int row = row0 + ai * HALF + m * 16;
;                 const float lrr = lz_ss ? rsqrtf(lr[ai][m] * (1.0f / DM) + RMS_EPS) : 1.0f;
;                 float s1 = 0.f, s2 = 0.f;
; #pragma unroll
;                 for (int bj = 0; bj < 2; ++bj) {
;                     const int col = col0 + bj * HALF; const size_t off = (size_t)row * DM + col;
;                     f32x4 r0, r1;
;                     if (resid_f32) { r0 = *(const f32x4*)(resid_f32 + off); r1 = *(const f32x4*)(resid_f32 + off + 4); }
;                     else { const u32x4 q = qb[m][bj];
;                         r0 = (f32x4){__uint_as_float(q.x << 16), __uint_as_float(q.x & 0xffff0000u), __uint_as_float(q.y << 16), __uint_as_float(q.y & 0xffff0000u)};
;                         r1 = (f32x4){__uint_as_float(q.z << 16), __uint_as_float(q.z & 0xffff0000u), __uint_as_float(q.w << 16), __uint_as_float(q.w & 0xffff0000u)}; }
;                     if (lz_ss) { const f32x4 g0 = *(const f32x4*)(lz_g + col), g1 = *(const f32x4*)(lz_g + col + 4); r0 = r0 * g0 * lrr; r1 = r1 * g1 * lrr; }
;                     const f32x4 x0 = r0 + acc[ai][bj][m][0] * alpha, x1 = r1 + acc[ai][bj][m][1] * alpha;
;                     u32x4 w; w.x = cvt_pk_bf16(x0[0], x0[1]); w.y = cvt_pk_bf16(x0[2], x0[3]); w.z = cvt_pk_bf16(x1[0], x1[1]); w.w = cvt_pk_bf16(x1[2], x1[3]);
;                     *(u32x4*)(xb + off) = w;
;                     s1 += ((x0[0] * x0[0] + x0[1] * x0[1]) + (x0[2] * x0[2] + x0[3] * x0[3])) + ((x1[0] * x1[0] + x1[1] * x1[1]) + (x1[2] * x1[2] + x1[3] * x1[3]));
;                     if (ss2) { const f32x4 a0 = *(const f32x4*)(ga + col), a1 = *(const f32x4*)(ga + col + 4); const f32x4 y0 = x0 * a0, y1 = x1 * a1;
;                         s2 += ((y0[0] * y0[0] + y0[1] * y0[1]) + (y0[2] * y0[2] + y0[3] * y0[3])) + ((y1[0] * y1[0] + y1[1] * y1[1]) + (y1[2] * y1[2] + y1[3] * y1[3])); }
;                 }
;                 s1 += __shfl_xor(s1, 16); s1 += __shfl_xor(s1, 32);
;                 if (fq == 0) ss_add(ss1 + row, s1);
;                 if (ss2) { s2 += __shfl_xor(s2, 16); s2 += __shfl_xor(s2, 32); if (fq == 0) ss_add(ss2 + row, s2); }
.LBB0_914:
	s_waitcnt vmcnt(0)
	v_pk_fma_f32 v[8:9], v[8:9], 0.5, v[16:17] op_sel_hi:[1,0,1]
	v_pk_fma_f32 v[6:7], v[6:7], 0.5, v[14:15] op_sel_hi:[1,0,1]
	v_pk_fma_f32 v[10:11], v[2:3], 0.5, v[10:11] op_sel_hi:[1,0,1]
	v_mul_f32_e32 v2, v7, v7
	v_mul_f32_e32 v3, v9, v9
	v_pk_fma_f32 v[12:13], v[4:5], 0.5, v[12:13] op_sel_hi:[1,0,1]
	v_fmac_f32_e32 v2, v6, v6
	v_fmac_f32_e32 v3, v8, v8
	v_mul_f32_e32 v26, v33, v33
	v_mul_f32_e32 v25, v25, v25
	v_mul_f32_e32 v23, v23, v23
	v_mul_f32_e32 v21, v21, v21
	v_add_f32_e32 v2, v2, v3
	v_mul_f32_e32 v3, v11, v11
	v_mul_f32_e32 v4, v13, v13
	v_fmac_f32_e32 v26, v32, v32
	v_fmac_f32_e32 v25, v24, v24
	v_fmac_f32_e32 v23, v22, v22
	v_fmac_f32_e32 v21, v20, v20
	v_fmac_f32_e32 v3, v10, v10
	v_fmac_f32_e32 v4, v12, v12
	v_add_f32_e32 v24, v26, v25
	v_add_f32_e32 v20, v23, v21
	v_add_f32_e32 v3, v3, v4
	v_add_f32_e32 v20, v20, v24
	v_add_f32_e32 v2, v3, v2
	v_add_f32_e32 v2, v20, v2
	ds_bpermute_b32 v3, v164, v2
	v_cvt_pk_bf16_f32 v4, v6, v7
	v_cvt_pk_bf16_f32 v5, v8, v9
	v_cvt_pk_bf16_f32 v6, v10, v11
	v_cvt_pk_bf16_f32 v7, v12, v13
	s_waitcnt lgkmcnt(0)
	v_add_f32_e32 v2, v2, v3
	ds_bpermute_b32 v3, v165, v2
	global_store_dwordx4 v[18:19], v[4:7], off offset:256
	s_and_saveexec_b64 s[6:7], s[54:55]
	s_cbranch_execz .LBB0_916
	s_waitcnt lgkmcnt(0)
	v_add_f32_e32 v2, v2, v3
	v_mul_f32_e32 v2, 0x49800000, v2
	v_rndne_f32_e32 v2, v2
	v_mul_f32_e64 v3, |v2|, s90
	v_floor_f32_e32 v3, v3
	v_fma_f32 v4, v3, s91, |v2|
	v_cvt_u32_f32_e32 v4, v4
	v_cvt_u32_f32_e32 v3, v3
	v_ashrrev_i32_e32 v5, 31, v2
	v_xor_b32_e32 v2, v4, v5
	v_xor_b32_e32 v3, v3, v5
	v_sub_co_u32_e32 v2, vcc, v2, v5
	s_nop 1
	v_subb_co_u32_e32 v3, vcc, v3, v5, vcc
	v_mbcnt_lo_u32_b32 v5, -1, 0
	v_lshlrev_b32_e32 v5, 3, v5
	v_add_u32_e32 v5, s24, v5
	v_add_u32_e32 v5, 0x20c00, v5
	ds_write_b64 v5, v[2:3] offset:896
.LBB0_916:
	s_or_b64 exec, exec, s[6:7]
	s_mov_b64 s[6:7], exec
	s_mov_b64 exec, 0xffff
	v_mbcnt_lo_u32_b32 v2, -1, 0
	v_lshlrev_b32_e32 v2, 3, v2
	v_add_u32_e32 v2, s24, v2
	v_add_u32_e32 v2, 0x20c00, v2
	ds_read_b64 v[4:5], v2
	ds_read_b64 v[6:7], v2 offset:128
	ds_read_b64 v[8:9], v2 offset:256
	ds_read_b64 v[10:11], v2 offset:384
	ds_read_b64 v[12:13], v2 offset:512
	ds_read_b64 v[14:15], v2 offset:640
	ds_read_b64 v[16:17], v2 offset:768
	ds_read_b64 v[18:19], v2 offset:896
	s_waitcnt lgkmcnt(0)
	global_atomic_add_x2 v[154:155], v[4:5], off
	global_atomic_add_x2 v[154:155], v[6:7], off offset:128
	global_atomic_add_x2 v[154:155], v[8:9], off offset:256
	global_atomic_add_x2 v[154:155], v[10:11], off offset:384
	global_atomic_add_x2 v[154:155], v[12:13], off offset:1024
	global_atomic_add_x2 v[154:155], v[14:15], off offset:1152
	global_atomic_add_x2 v[154:155], v[16:17], off offset:1280
	global_atomic_add_x2 v[154:155], v[18:19], off offset:1408
	s_mov_b64 exec, s[6:7]
	s_and_b64 vcc, exec, s[56:57]
	s_mov_b64 s[6:7], -1
	s_cbranch_vccnz .LBB0_783
	s_andn2_b64 vcc, exec, s[64:65]
	s_cbranch_vccnz .LBB0_782
	s_barrier
	s_branch .LBB0_782
